# attention steady loop: the canonicalize+max head of each row-max chain folded into one v_max_f32 (3 -> 1 instructions, twice per trip); placement of later loops kept by padding
# speedup vs baseline: 1.0051x; 1.0006x over previous
.LBB0_563:
	v_add_u32_e32 v0, s12, v194
	ds_read_b64_tr_b16 v[168:169], v0 offset:24576
	ds_read_b64_tr_b16 v[170:171], v0 offset:25088
	s_waitcnt lgkmcnt(5)
	v_mfma_f32_32x32x16_bf16 v[112:127], v[164:167], v[144:147], v[48:63]
	v_add_f32_e32 v2, v80, v81
	v_add_f32_e32 v2, v82, v2
	v_add_f32_e32 v2, v83, v2
	v_add_f32_e32 v2, v84, v2
	v_add_f32_e32 v2, v85, v2
	v_cvt_pk_bf16_f32 v148, v80, v81
	v_cvt_pk_bf16_f32 v149, v82, v83
	ds_read_b64_tr_b16 v[164:165], v0 offset:28672
	ds_read_b64_tr_b16 v[166:167], v0 offset:29184
	s_waitcnt lgkmcnt(6)
	v_mfma_f32_32x32x16_bf16 v[96:111], v[160:163], v[144:147], v[48:63]
	v_add_f32_e32 v2, v86, v2
	v_add_f32_e32 v2, v87, v2
	v_add_f32_e32 v2, v88, v2
	v_add_f32_e32 v2, v89, v2
	v_cvt_pk_bf16_f32 v150, v84, v85
	v_cvt_pk_bf16_f32 v151, v86, v87
	ds_read_b64_tr_b16 v[6:7], v0 offset:25600
	ds_read_b64_tr_b16 v[8:9], v0 offset:26112
	s_waitcnt lgkmcnt(7)
	v_mfma_f32_32x32x16_bf16 v[112:127], v[156:159], v[136:139], v[112:127]
	v_add_f32_e32 v2, v90, v2
	v_add_f32_e32 v2, v91, v2
	v_add_f32_e32 v2, v92, v2
	v_add_f32_e32 v2, v93, v2
	v_cvt_pk_bf16_f32 v140, v88, v89
	v_cvt_pk_bf16_f32 v141, v90, v91
	ds_read_b64_tr_b16 v[80:81], v0 offset:29696
	ds_read_b64_tr_b16 v[82:83], v0 offset:30208
	s_waitcnt lgkmcnt(8)
	v_mfma_f32_32x32x16_bf16 v[96:111], v[152:155], v[136:139], v[96:111]
	v_add_f32_e32 v2, v94, v2
	v_add_f32_e32 v2, v95, v2
	v_add_f32_e32 v2, v64, v2
	v_add_f32_e32 v2, v65, v2
	v_cvt_pk_bf16_f32 v142, v92, v93
	v_cvt_pk_bf16_f32 v143, v94, v95
	ds_read_b64_tr_b16 v[84:85], v0 offset:26624
	ds_read_b64_tr_b16 v[86:87], v0 offset:27136
	v_add_f32_e32 v2, v66, v2
	v_add_f32_e32 v2, v67, v2
	v_add_f32_e32 v2, v68, v2
	v_add_f32_e32 v2, v69, v2
	v_cvt_pk_bf16_f32 v132, v64, v65
	v_cvt_pk_bf16_f32 v133, v66, v67
	ds_read_b64_tr_b16 v[64:65], v0 offset:30720
	ds_read_b64_tr_b16 v[66:67], v0 offset:31232
	v_add_f32_e32 v2, v70, v2
	v_add_f32_e32 v2, v71, v2
	v_add_f32_e32 v2, v72, v2
	v_add_f32_e32 v2, v73, v2
	v_cvt_pk_bf16_f32 v134, v68, v69
	v_cvt_pk_bf16_f32 v135, v70, v71
	ds_read_b64_tr_b16 v[10:11], v0 offset:27648
	ds_read_b64_tr_b16 v[12:13], v0 offset:28160
	v_add_f32_e32 v2, v74, v2
	v_add_f32_e32 v2, v75, v2
	v_add_f32_e32 v2, v76, v2
	v_add_f32_e32 v14, v77, v2
	v_cvt_pk_bf16_f32 v128, v72, v73
	v_cvt_pk_bf16_f32 v129, v74, v75
	ds_read_b64_tr_b16 v[2:3], v0 offset:31744
	ds_read_b64_tr_b16 v[4:5], v0 offset:32256
	v_add_f32_e32 v0, v78, v14
	v_add_f32_e32 v0, v79, v0
	v_cvt_pk_bf16_f32 v130, v76, v77
	v_cvt_pk_bf16_f32 v131, v78, v79
	v_lshl_add_u64 v[14:15], v[178:179], 0, s[50:51]
	s_add_i32 s12, s3, s75
	s_mov_b32 s13, m0
	s_mov_b32 m0, s12
	s_nop 0
	global_load_lds_dwordx4 v[14:15], off
	s_mov_b32 m0, s13
	s_mov_b32 s12, 0xfffb0000
	s_mov_b32 s13, -1
	v_lshl_add_u64 v[14:15], v[176:177], 0, s[12:13]
	s_add_i32 s12, s16, s76
	s_mov_b32 s13, m0
	s_mov_b32 m0, s12
	s_nop 0
	global_load_lds_dwordx4 v[14:15], off
	s_mov_b32 m0, s13
	v_max_f32_e32 v14, v112, v113
	v_max3_f32 v15, v114, v115, v97
	v_max3_f32 v14, v14, v96, v98
	v_max3_f32 v14, v14, v99, v116
	v_max3_f32 v15, v15, v118, v119
	v_max3_f32 v14, v14, v117, v100
	v_max3_f32 v15, v15, v102, v103
	v_max3_f32 v14, v14, v101, v120
	v_max3_f32 v15, v15, v122, v123
	v_max3_f32 v14, v14, v121, v104
	v_max3_f32 v15, v15, v106, v107
	v_max3_f32 v14, v14, v105, v124
	v_max3_f32 v15, v15, v126, v127
	v_max3_f32 v68, v14, v125, v108
	v_max3_f32 v15, v15, v110, v111
	v_add_f32_e32 v14, v196, v0
	v_max3_f32 v0, v68, v109, v15
	v_mov_b32_e32 v15, v0
	s_nop 1
	v_permlane32_swap_b32_e32 v0, v15
	v_max_f32_e32 v0, v0, v15
	v_cmp_lt_f32_e32 vcc, s58, v0
	s_cmp_lg_u64 vcc, 0
	s_cselect_b64 s[12:13], -1, 0
	s_cbranch_vccnz .LBB0_571

.LBB0_566:
	s_add_i32 s12, s16, 0x2000
	s_cmpk_lg_i32 s16, 0x4000
	s_cselect_b32 s78, s12, 0
	v_add_u32_e32 v4, s3, v194
	ds_read_b64_tr_b16 v[156:157], v4 offset:24576
	ds_read_b64_tr_b16 v[158:159], v4 offset:25088
	s_waitcnt lgkmcnt(5)
	v_mfma_f32_32x32x16_bf16 v[80:95], v[68:71], v[144:147], v[48:63]
	v_add_f32_e32 v2, v112, v113
	v_add_f32_e32 v2, v114, v2
	v_add_f32_e32 v2, v115, v2
	v_add_f32_e32 v2, v116, v2
	v_add_f32_e32 v2, v117, v2
	v_cvt_pk_bf16_f32 v148, v112, v113
	v_cvt_pk_bf16_f32 v149, v114, v115
	ds_read_b64_tr_b16 v[152:153], v4 offset:28672
	ds_read_b64_tr_b16 v[154:155], v4 offset:29184
	s_waitcnt lgkmcnt(6)
	v_mfma_f32_32x32x16_bf16 v[64:79], v[164:167], v[144:147], v[48:63]
	v_add_f32_e32 v2, v118, v2
	v_add_f32_e32 v2, v119, v2
	v_add_f32_e32 v2, v120, v2
	v_add_f32_e32 v2, v121, v2
	v_cvt_pk_bf16_f32 v150, v116, v117
	v_cvt_pk_bf16_f32 v151, v118, v119
	ds_read_b64_tr_b16 v[6:7], v4 offset:25600
	ds_read_b64_tr_b16 v[8:9], v4 offset:26112
	s_waitcnt lgkmcnt(7)
	v_mfma_f32_32x32x16_bf16 v[80:95], v[168:171], v[136:139], v[80:95]
	v_add_f32_e32 v2, v122, v2
	v_add_f32_e32 v2, v123, v2
	v_add_f32_e32 v2, v124, v2
	v_add_f32_e32 v2, v125, v2
	v_cvt_pk_bf16_f32 v140, v120, v121
	v_cvt_pk_bf16_f32 v141, v122, v123
	ds_read_b64_tr_b16 v[112:113], v4 offset:29696
	ds_read_b64_tr_b16 v[114:115], v4 offset:30208
	s_waitcnt lgkmcnt(8)
	v_mfma_f32_32x32x16_bf16 v[64:79], v[160:163], v[136:139], v[64:79]
	v_add_f32_e32 v2, v126, v2
	v_add_f32_e32 v2, v127, v2
	v_add_f32_e32 v2, v96, v2
	v_add_f32_e32 v2, v97, v2
	v_cvt_pk_bf16_f32 v142, v124, v125
	v_cvt_pk_bf16_f32 v143, v126, v127
	ds_read_b64_tr_b16 v[116:117], v4 offset:26624
	ds_read_b64_tr_b16 v[118:119], v4 offset:27136
	v_add_f32_e32 v2, v98, v2
	v_add_f32_e32 v2, v99, v2
	v_add_f32_e32 v2, v100, v2
	v_add_f32_e32 v2, v101, v2
	v_cvt_pk_bf16_f32 v132, v96, v97
	v_cvt_pk_bf16_f32 v133, v98, v99
	ds_read_b64_tr_b16 v[96:97], v4 offset:30720
	ds_read_b64_tr_b16 v[98:99], v4 offset:31232
	v_add_f32_e32 v2, v102, v2
	v_add_f32_e32 v2, v103, v2
	v_add_f32_e32 v2, v104, v2
	v_add_f32_e32 v2, v105, v2
	v_cvt_pk_bf16_f32 v134, v100, v101
	v_cvt_pk_bf16_f32 v135, v102, v103
	ds_read_b64_tr_b16 v[10:11], v4 offset:27648
	ds_read_b64_tr_b16 v[12:13], v4 offset:28160
	v_add_f32_e32 v2, v106, v2
	v_add_f32_e32 v2, v107, v2
	v_add_f32_e32 v2, v108, v2
	v_add_f32_e32 v15, v109, v2
	v_cvt_pk_bf16_f32 v128, v104, v105
	v_cvt_pk_bf16_f32 v129, v106, v107
	ds_read_b64_tr_b16 v[2:3], v4 offset:31744
	ds_read_b64_tr_b16 v[4:5], v4 offset:32256
	v_add_f32_e32 v15, v110, v15
	v_add_f32_e32 v15, v111, v15
	v_cvt_pk_bf16_f32 v130, v108, v109
	v_cvt_pk_bf16_f32 v131, v110, v111
	v_max_f32_e32 v100, v80, v81
	v_max3_f32 v101, v82, v83, v65
	v_max3_f32 v100, v100, v64, v66
	v_max3_f32 v100, v100, v67, v84
	v_max3_f32 v101, v101, v86, v87
	v_max3_f32 v100, v100, v85, v68
	v_max3_f32 v101, v101, v70, v71
	v_max3_f32 v100, v100, v69, v88
	v_max3_f32 v101, v101, v90, v91
	v_max3_f32 v100, v100, v89, v72
	v_max3_f32 v101, v101, v74, v75
	v_max3_f32 v100, v100, v73, v92
	v_max3_f32 v101, v101, v94, v95
	v_max3_f32 v100, v100, v93, v76
	v_max3_f32 v101, v101, v78, v79
	v_add_f32_e32 v196, v14, v15
	v_max3_f32 v14, v100, v77, v101
	v_mov_b32_e32 v15, v14
	s_nop 1
	v_permlane32_swap_b32_e32 v14, v15
	s_add_i32 s3, s16, s75
	s_mov_b32 s12, m0
	s_mov_b32 m0, s3
	s_nop 0
	global_load_lds_dwordx4 v[178:179], off
	s_mov_b32 m0, s12
	v_max_f32_e32 v14, v14, v15
	s_add_i32 s3, s78, s76
	s_mov_b32 s12, m0
	s_mov_b32 m0, s3
	s_nop 0
	global_load_lds_dwordx4 v[176:177], off
	s_mov_b32 m0, s12
	v_cmp_lt_f32_e32 vcc, s58, v14
	s_cmp_lg_u64 vcc, 0
	s_cselect_b64 s[12:13], -1, 0
	s_cbranch_vccnz .LBB0_574

; __device__ __forceinline__ unsigned xb_add(unsigned* p, unsigned v) { return __hip_atomic_fetch_add(p, v, __ATOMIC_RELAXED, __HIP_MEMORY_SCOPE_AGENT); }
; __device__ __forceinline__ void xcd_barrier(const XcdBarrier& b) {
;     asm volatile("s_waitcnt vmcnt(0)" ::: "memory");
;     __syncthreads();
;     if (threadIdx.x == 0) {
;         unsigned* bar = b.bar;
;         __builtin_amdgcn_s_waitcnt(0);
;         unsigned nloc = b.st[0], nx = b.st[1];
;         if (nloc == 0u) { xcd_barrier_complete(bar, b.x, nloc, nx); b.st[0] = nloc; b.st[1] = nx; }
;         const unsigned old = xb_add(&bar[XB_XSUB(b.x)], 1u);
;         const unsigned gen = old / nloc;
.LBB0_633:
	s_nop 0
	s_nop 0
	s_nop 0
	s_nop 0
	s_nop 0
	s_nop 0
	s_nop 0
	s_nop 0
	s_nop 0
	s_nop 0
	s_mov_b64 s[6:7], s[0:1]
	s_getreg_b32 s2, hwreg(HW_REG_XCC_ID, 0, 4)
	s_waitcnt vmcnt(0)
	s_barrier
	s_mov_b64 s[4:5], exec
	v_readlane_b32 s8, v255, 0
	v_readlane_b32 s9, v255, 1
	s_and_b64 s[8:9], s[4:5], s[8:9]
	v_readlane_b32 s41, v255, 10
	s_movk_i32 s42, 0x1000
	s_mov_b64 s[48:49], 0x1200
	s_mov_b32 s62, 0x3c800000
	s_mov_b64 exec, s[8:9]
	s_cbranch_execz .LBB0_685
	v_readlane_b32 s3, v255, 2
	s_load_dwordx2 s[6:7], s[6:7], 0x118
	s_waitcnt vmcnt(0) expcnt(0) lgkmcnt(0)
	v_mov_b32_e32 v0, s3
	ds_read_b32 v3, v0
	v_readlane_b32 s3, v255, 3
	s_and_b32 s2, s2, 15
	s_waitcnt lgkmcnt(0)
	v_cmp_ne_u32_e32 vcc, 0, v3
	v_mov_b32_e32 v0, s3
	ds_read_b32 v0, v0
	s_cbranch_vccnz .LBB0_649
	s_add_u32 s8, s6, 0x1000
	s_addc_u32 s9, s7, 0
	s_add_u32 s10, s6, 0x1100
	s_addc_u32 s11, s7, 0
	s_add_u32 s12, s6, 0x1200
	s_addc_u32 s13, s7, 0
	s_add_u32 s14, s6, 0x1300
	s_addc_u32 s15, s7, 0
	s_mov_b32 s3, 1
	s_branch .LBB0_637
